# merge K-loop hand-scheduled: 10 rotating fragment slots (4 borrowed from hoisted constants), every LDS read issued 4+ MFMAs ahead, barrier after row 1 of second half-step
# speedup vs baseline: 1.0028x; 1.0020x over previous
.LBB0_1010:
	ds_read_b128 v[90:93], v119 offset:0
	ds_read_b128 v[208:211], v119 offset:2560
	ds_read_b128 v[212:215], v119 offset:5120
	ds_read_b128 v[216:219], v119 offset:7680
	ds_read_b128 v[220:223], v205 offset:0
	ds_read_b128 v[224:227], v205 offset:2560
	ds_read_b128 v[138:141], v205 offset:5120
	ds_read_b128 v[142:145], v205 offset:7680
	ds_read_b128 v[146:149], v119 offset:64
	ds_read_b128 v[194:197], v119 offset:2624
	s_waitcnt lgkmcnt(5)
	v_mfma_f32_16x16x32_bf16 v[6:9], v[90:93], v[220:223], v[6:9]
	v_mfma_f32_16x16x32_bf16 v[30:33], v[208:211], v[220:223], v[30:33]
	s_waitcnt vmcnt(11)
	ds_write_b128 v207, v[228:231] offset:0
	v_mfma_f32_16x16x32_bf16 v[38:41], v[212:215], v[220:223], v[38:41]
	v_mfma_f32_16x16x32_bf16 v[42:45], v[216:219], v[220:223], v[42:45]
	ds_read_b128 v[220:223], v205 offset:64
	s_waitcnt lgkmcnt(6)
	v_mfma_f32_16x16x32_bf16 v[46:49], v[90:93], v[224:227], v[46:49]
	s_waitcnt vmcnt(10)
	ds_write_b128 v207, v[232:235] offset:10240
	v_mfma_f32_16x16x32_bf16 v[26:29], v[208:211], v[224:227], v[26:29]
	v_mfma_f32_16x16x32_bf16 v[14:17], v[212:215], v[224:227], v[14:17]
	v_mfma_f32_16x16x32_bf16 v[10:13], v[216:219], v[224:227], v[10:13]
	s_waitcnt vmcnt(9)
	ds_write_b128 v207, v[236:239] offset:20480
	ds_read_b128 v[224:227], v205 offset:2624
	s_waitcnt lgkmcnt(8)
	v_mfma_f32_16x16x32_bf16 v[34:37], v[90:93], v[138:141], v[34:37]
	v_mfma_f32_16x16x32_bf16 v[22:25], v[208:211], v[138:141], v[22:25]
	v_mfma_f32_16x16x32_bf16 v[18:21], v[212:215], v[138:141], v[18:21]
	s_waitcnt vmcnt(8)
	ds_write_b128 v207, v[240:243] offset:30720
	v_mfma_f32_16x16x32_bf16 v[62:65], v[216:219], v[138:141], v[62:65]
	ds_read_b128 v[138:141], v205 offset:5184
	s_waitcnt lgkmcnt(9)
	v_mfma_f32_16x16x32_bf16 v[50:53], v[212:215], v[142:145], v[50:53]
	ds_read_b128 v[212:215], v119 offset:5184
	v_mfma_f32_16x16x32_bf16 v[2:5], v[216:219], v[142:145], v[2:5]
	s_waitcnt vmcnt(7)
	ds_write_b128 v0, v[244:247] offset:20480
	ds_read_b128 v[216:219], v119 offset:7744
	v_mfma_f32_16x16x32_bf16 v[58:61], v[90:93], v[142:145], v[58:61]
	v_mfma_f32_16x16x32_bf16 v[54:57], v[208:211], v[142:145], v[54:57]
	ds_read_b128 v[142:145], v205 offset:7744
	s_waitcnt lgkmcnt(9)
	v_mfma_f32_16x16x32_bf16 v[6:9], v[146:149], v[220:223], v[6:9]
	s_waitcnt vmcnt(6)
	ds_write_b128 v0, v[248:251] offset:30720
	v_mfma_f32_16x16x32_bf16 v[30:33], v[194:197], v[220:223], v[30:33]
	s_waitcnt lgkmcnt(4)
	v_mfma_f32_16x16x32_bf16 v[38:41], v[212:215], v[220:223], v[38:41]
	s_waitcnt lgkmcnt(2)
	v_mfma_f32_16x16x32_bf16 v[42:45], v[216:219], v[220:223], v[42:45]
	v_mfma_f32_16x16x32_bf16 v[46:49], v[146:149], v[224:227], v[46:49]
	v_mfma_f32_16x16x32_bf16 v[26:29], v[194:197], v[224:227], v[26:29]
	v_mfma_f32_16x16x32_bf16 v[14:17], v[212:215], v[224:227], v[14:17]
	v_mfma_f32_16x16x32_bf16 v[10:13], v[216:219], v[224:227], v[10:13]
	s_waitcnt lgkmcnt(0)
	s_barrier
	ds_read_b128 v[90:93], v205 offset:40960
	ds_read_b128 v[208:211], v205 offset:43520
	ds_read_b128 v[220:223], v119 offset:20480
	ds_read_b128 v[224:227], v119 offset:23040
	v_mfma_f32_16x16x32_bf16 v[34:37], v[146:149], v[138:141], v[34:37]
	v_mfma_f32_16x16x32_bf16 v[22:25], v[194:197], v[138:141], v[22:25]
	v_mfma_f32_16x16x32_bf16 v[18:21], v[212:215], v[138:141], v[18:21]
	v_mfma_f32_16x16x32_bf16 v[62:65], v[216:219], v[138:141], v[62:65]
	ds_read_b128 v[138:141], v205 offset:46080
	v_mfma_f32_16x16x32_bf16 v[50:53], v[212:215], v[142:145], v[50:53]
	ds_read_b128 v[212:215], v119 offset:25600
	v_mfma_f32_16x16x32_bf16 v[2:5], v[216:219], v[142:145], v[2:5]
	ds_read_b128 v[216:219], v119 offset:28160
	v_mfma_f32_16x16x32_bf16 v[58:61], v[146:149], v[142:145], v[58:61]
	v_mfma_f32_16x16x32_bf16 v[54:57], v[194:197], v[142:145], v[54:57]
	ds_read_b128 v[142:145], v205 offset:48640
	ds_read_b128 v[146:149], v119 offset:20544
	ds_read_b128 v[194:197], v119 offset:23104
	global_load_dwordx4 v[228:231], v190, s[80:81] offset:384
	global_load_dwordx4 v[232:235], v191, s[80:81] offset:384
	global_load_dwordx4 v[236:239], v190, s[86:87] offset:384
	global_load_dwordx4 v[240:243], v191, s[86:87] offset:384
	global_load_dwordx4 v[244:247], v188, s[96:97] offset:384
	global_load_dwordx4 v[248:251], v188, s[98:99] offset:384
	s_waitcnt lgkmcnt(7)
	v_mfma_f32_16x16x32_bf16 v[6:9], v[220:223], v[90:93], v[6:9]
	s_waitcnt lgkmcnt(6)
	v_mfma_f32_16x16x32_bf16 v[30:33], v[224:227], v[90:93], v[30:33]
	s_waitcnt vmcnt(11)
	ds_write_b128 v206, v[66:69] offset:0
	s_waitcnt lgkmcnt(5)
	v_mfma_f32_16x16x32_bf16 v[38:41], v[212:215], v[90:93], v[38:41]
	s_waitcnt lgkmcnt(4)
	v_mfma_f32_16x16x32_bf16 v[42:45], v[216:219], v[90:93], v[42:45]
	ds_read_b128 v[90:93], v205 offset:41024
	v_mfma_f32_16x16x32_bf16 v[46:49], v[220:223], v[208:211], v[46:49]
	s_waitcnt vmcnt(10)
	ds_write_b128 v206, v[70:73] offset:10240
	v_mfma_f32_16x16x32_bf16 v[26:29], v[224:227], v[208:211], v[26:29]
	v_mfma_f32_16x16x32_bf16 v[14:17], v[212:215], v[208:211], v[14:17]
	v_mfma_f32_16x16x32_bf16 v[10:13], v[216:219], v[208:211], v[10:13]
	s_waitcnt vmcnt(9)
	ds_write_b128 v206, v[74:77] offset:20480
	ds_read_b128 v[208:211], v205 offset:43584
	v_mfma_f32_16x16x32_bf16 v[34:37], v[220:223], v[138:141], v[34:37]
	v_mfma_f32_16x16x32_bf16 v[22:25], v[224:227], v[138:141], v[22:25]
	v_mfma_f32_16x16x32_bf16 v[18:21], v[212:215], v[138:141], v[18:21]
	s_waitcnt vmcnt(8)
	ds_write_b128 v206, v[78:81] offset:30720
	v_mfma_f32_16x16x32_bf16 v[62:65], v[216:219], v[138:141], v[62:65]
	ds_read_b128 v[138:141], v205 offset:46144
	s_waitcnt lgkmcnt(9)
	v_mfma_f32_16x16x32_bf16 v[50:53], v[212:215], v[142:145], v[50:53]
	ds_read_b128 v[212:215], v119 offset:25664
	v_mfma_f32_16x16x32_bf16 v[2:5], v[216:219], v[142:145], v[2:5]
	s_waitcnt vmcnt(7)
	ds_write_b128 v0, v[82:85] offset:0
	ds_read_b128 v[216:219], v119 offset:28224
	v_mfma_f32_16x16x32_bf16 v[58:61], v[220:223], v[142:145], v[58:61]
	v_mfma_f32_16x16x32_bf16 v[54:57], v[224:227], v[142:145], v[54:57]
	ds_read_b128 v[142:145], v205 offset:48704
	s_waitcnt lgkmcnt(9)
	v_mfma_f32_16x16x32_bf16 v[6:9], v[146:149], v[90:93], v[6:9]
	s_waitcnt vmcnt(6)
	ds_write_b128 v0, v[86:89] offset:10240
	v_mfma_f32_16x16x32_bf16 v[30:33], v[194:197], v[90:93], v[30:33]
	s_waitcnt lgkmcnt(4)
	v_mfma_f32_16x16x32_bf16 v[38:41], v[212:215], v[90:93], v[38:41]
	s_waitcnt lgkmcnt(2)
	v_mfma_f32_16x16x32_bf16 v[42:45], v[216:219], v[90:93], v[42:45]
	v_mfma_f32_16x16x32_bf16 v[46:49], v[146:149], v[208:211], v[46:49]
	v_mfma_f32_16x16x32_bf16 v[26:29], v[194:197], v[208:211], v[26:29]
	v_mfma_f32_16x16x32_bf16 v[14:17], v[212:215], v[208:211], v[14:17]
	v_mfma_f32_16x16x32_bf16 v[10:13], v[216:219], v[208:211], v[10:13]
	s_waitcnt lgkmcnt(0)
	s_barrier
	ds_read_b128 v[220:223], v205 offset:0
	ds_read_b128 v[224:227], v205 offset:2560
	ds_read_b128 v[90:93], v119 offset:0
	ds_read_b128 v[208:211], v119 offset:2560
	v_mfma_f32_16x16x32_bf16 v[34:37], v[146:149], v[138:141], v[34:37]
	v_mfma_f32_16x16x32_bf16 v[22:25], v[194:197], v[138:141], v[22:25]
	v_mfma_f32_16x16x32_bf16 v[18:21], v[212:215], v[138:141], v[18:21]
	v_mfma_f32_16x16x32_bf16 v[62:65], v[216:219], v[138:141], v[62:65]
	ds_read_b128 v[138:141], v205 offset:5120
	v_mfma_f32_16x16x32_bf16 v[50:53], v[212:215], v[142:145], v[50:53]
	ds_read_b128 v[212:215], v119 offset:5120
	v_mfma_f32_16x16x32_bf16 v[2:5], v[216:219], v[142:145], v[2:5]
	ds_read_b128 v[216:219], v119 offset:7680
	v_mfma_f32_16x16x32_bf16 v[58:61], v[146:149], v[142:145], v[58:61]
	v_mfma_f32_16x16x32_bf16 v[54:57], v[194:197], v[142:145], v[54:57]
	ds_read_b128 v[142:145], v205 offset:7680
	ds_read_b128 v[146:149], v119 offset:64
	ds_read_b128 v[194:197], v119 offset:2624
	global_load_dwordx4 v[66:69], v190, s[80:81] offset:512
	global_load_dwordx4 v[70:73], v191, s[80:81] offset:512
	global_load_dwordx4 v[74:77], v190, s[86:87] offset:512
	global_load_dwordx4 v[78:81], v191, s[86:87] offset:512
	global_load_dwordx4 v[82:85], v188, s[96:97] offset:512
	global_load_dwordx4 v[86:89], v188, s[98:99] offset:512
	s_waitcnt lgkmcnt(7)
	v_mfma_f32_16x16x32_bf16 v[6:9], v[90:93], v[220:223], v[6:9]
	s_waitcnt lgkmcnt(6)
	v_mfma_f32_16x16x32_bf16 v[30:33], v[208:211], v[220:223], v[30:33]
	s_waitcnt vmcnt(11)
	ds_write_b128 v207, v[228:231] offset:0
	s_waitcnt lgkmcnt(5)
	v_mfma_f32_16x16x32_bf16 v[38:41], v[212:215], v[220:223], v[38:41]
	s_waitcnt lgkmcnt(4)
	v_mfma_f32_16x16x32_bf16 v[42:45], v[216:219], v[220:223], v[42:45]
	ds_read_b128 v[220:223], v205 offset:64
	v_mfma_f32_16x16x32_bf16 v[46:49], v[90:93], v[224:227], v[46:49]
	s_waitcnt vmcnt(10)
	ds_write_b128 v207, v[232:235] offset:10240
	v_mfma_f32_16x16x32_bf16 v[26:29], v[208:211], v[224:227], v[26:29]
	v_mfma_f32_16x16x32_bf16 v[14:17], v[212:215], v[224:227], v[14:17]
	v_mfma_f32_16x16x32_bf16 v[10:13], v[216:219], v[224:227], v[10:13]
	s_waitcnt vmcnt(9)
	ds_write_b128 v207, v[236:239] offset:20480
	ds_read_b128 v[224:227], v205 offset:2624
	v_mfma_f32_16x16x32_bf16 v[34:37], v[90:93], v[138:141], v[34:37]
	v_mfma_f32_16x16x32_bf16 v[22:25], v[208:211], v[138:141], v[22:25]
	v_mfma_f32_16x16x32_bf16 v[18:21], v[212:215], v[138:141], v[18:21]
	s_waitcnt vmcnt(8)
	ds_write_b128 v207, v[240:243] offset:30720
	v_mfma_f32_16x16x32_bf16 v[62:65], v[216:219], v[138:141], v[62:65]
	ds_read_b128 v[138:141], v205 offset:5184
	s_waitcnt lgkmcnt(9)
	v_mfma_f32_16x16x32_bf16 v[50:53], v[212:215], v[142:145], v[50:53]
	ds_read_b128 v[212:215], v119 offset:5184
	v_mfma_f32_16x16x32_bf16 v[2:5], v[216:219], v[142:145], v[2:5]
	s_waitcnt vmcnt(7)
	ds_write_b128 v0, v[244:247] offset:20480
	ds_read_b128 v[216:219], v119 offset:7744
	v_mfma_f32_16x16x32_bf16 v[58:61], v[90:93], v[142:145], v[58:61]
	v_mfma_f32_16x16x32_bf16 v[54:57], v[208:211], v[142:145], v[54:57]
	ds_read_b128 v[142:145], v205 offset:7744
	s_waitcnt lgkmcnt(9)
	v_mfma_f32_16x16x32_bf16 v[6:9], v[146:149], v[220:223], v[6:9]
	s_waitcnt vmcnt(6)
	ds_write_b128 v0, v[248:251] offset:30720
	v_mfma_f32_16x16x32_bf16 v[30:33], v[194:197], v[220:223], v[30:33]
	s_waitcnt lgkmcnt(4)
	v_mfma_f32_16x16x32_bf16 v[38:41], v[212:215], v[220:223], v[38:41]
	s_waitcnt lgkmcnt(2)
	v_mfma_f32_16x16x32_bf16 v[42:45], v[216:219], v[220:223], v[42:45]
	v_mfma_f32_16x16x32_bf16 v[46:49], v[146:149], v[224:227], v[46:49]
	v_mfma_f32_16x16x32_bf16 v[26:29], v[194:197], v[224:227], v[26:29]
	v_mfma_f32_16x16x32_bf16 v[14:17], v[212:215], v[224:227], v[14:17]
	v_mfma_f32_16x16x32_bf16 v[10:13], v[216:219], v[224:227], v[10:13]
	s_waitcnt lgkmcnt(0)
	s_barrier
	ds_read_b128 v[90:93], v205 offset:40960
	ds_read_b128 v[208:211], v205 offset:43520
	ds_read_b128 v[220:223], v119 offset:20480
	ds_read_b128 v[224:227], v119 offset:23040
	v_mfma_f32_16x16x32_bf16 v[34:37], v[146:149], v[138:141], v[34:37]
	v_mfma_f32_16x16x32_bf16 v[22:25], v[194:197], v[138:141], v[22:25]
	v_mfma_f32_16x16x32_bf16 v[18:21], v[212:215], v[138:141], v[18:21]
	v_mfma_f32_16x16x32_bf16 v[62:65], v[216:219], v[138:141], v[62:65]
	ds_read_b128 v[138:141], v205 offset:46080
	v_mfma_f32_16x16x32_bf16 v[50:53], v[212:215], v[142:145], v[50:53]
	ds_read_b128 v[212:215], v119 offset:25600
	v_mfma_f32_16x16x32_bf16 v[2:5], v[216:219], v[142:145], v[2:5]
	ds_read_b128 v[216:219], v119 offset:28160
	v_mfma_f32_16x16x32_bf16 v[58:61], v[146:149], v[142:145], v[58:61]
	v_mfma_f32_16x16x32_bf16 v[54:57], v[194:197], v[142:145], v[54:57]
	ds_read_b128 v[142:145], v205 offset:48640
	ds_read_b128 v[146:149], v119 offset:20544
	ds_read_b128 v[194:197], v119 offset:23104
	global_load_dwordx4 v[228:231], v190, s[80:81] offset:640
	global_load_dwordx4 v[232:235], v191, s[80:81] offset:640
	global_load_dwordx4 v[236:239], v190, s[86:87] offset:640
	global_load_dwordx4 v[240:243], v191, s[86:87] offset:640
	global_load_dwordx4 v[244:247], v188, s[96:97] offset:640
	global_load_dwordx4 v[248:251], v188, s[98:99] offset:640
	s_waitcnt lgkmcnt(7)
	v_mfma_f32_16x16x32_bf16 v[6:9], v[220:223], v[90:93], v[6:9]
	s_waitcnt lgkmcnt(6)
	v_mfma_f32_16x16x32_bf16 v[30:33], v[224:227], v[90:93], v[30:33]
	s_waitcnt vmcnt(11)
	ds_write_b128 v206, v[66:69] offset:0
	s_waitcnt lgkmcnt(5)
	v_mfma_f32_16x16x32_bf16 v[38:41], v[212:215], v[90:93], v[38:41]
	s_waitcnt lgkmcnt(4)
	v_mfma_f32_16x16x32_bf16 v[42:45], v[216:219], v[90:93], v[42:45]
	ds_read_b128 v[90:93], v205 offset:41024
	v_mfma_f32_16x16x32_bf16 v[46:49], v[220:223], v[208:211], v[46:49]
	s_waitcnt vmcnt(10)
	ds_write_b128 v206, v[70:73] offset:10240
	v_mfma_f32_16x16x32_bf16 v[26:29], v[224:227], v[208:211], v[26:29]
	v_mfma_f32_16x16x32_bf16 v[14:17], v[212:215], v[208:211], v[14:17]
	v_mfma_f32_16x16x32_bf16 v[10:13], v[216:219], v[208:211], v[10:13]
	s_waitcnt vmcnt(9)
	ds_write_b128 v206, v[74:77] offset:20480
	ds_read_b128 v[208:211], v205 offset:43584
	v_mfma_f32_16x16x32_bf16 v[34:37], v[220:223], v[138:141], v[34:37]
	v_mfma_f32_16x16x32_bf16 v[22:25], v[224:227], v[138:141], v[22:25]
	v_mfma_f32_16x16x32_bf16 v[18:21], v[212:215], v[138:141], v[18:21]
	s_waitcnt vmcnt(8)
	ds_write_b128 v206, v[78:81] offset:30720
	v_mfma_f32_16x16x32_bf16 v[62:65], v[216:219], v[138:141], v[62:65]
	ds_read_b128 v[138:141], v205 offset:46144
	s_waitcnt lgkmcnt(9)
	v_mfma_f32_16x16x32_bf16 v[50:53], v[212:215], v[142:145], v[50:53]
	ds_read_b128 v[212:215], v119 offset:25664
	v_mfma_f32_16x16x32_bf16 v[2:5], v[216:219], v[142:145], v[2:5]
	s_waitcnt vmcnt(7)
	ds_write_b128 v0, v[82:85] offset:0
	ds_read_b128 v[216:219], v119 offset:28224
	v_mfma_f32_16x16x32_bf16 v[58:61], v[220:223], v[142:145], v[58:61]
	v_mfma_f32_16x16x32_bf16 v[54:57], v[224:227], v[142:145], v[54:57]
	ds_read_b128 v[142:145], v205 offset:48704
	s_waitcnt lgkmcnt(9)
	v_mfma_f32_16x16x32_bf16 v[6:9], v[146:149], v[90:93], v[6:9]
	s_waitcnt vmcnt(6)
	ds_write_b128 v0, v[86:89] offset:10240
	v_mfma_f32_16x16x32_bf16 v[30:33], v[194:197], v[90:93], v[30:33]
	s_waitcnt lgkmcnt(4)
	v_mfma_f32_16x16x32_bf16 v[38:41], v[212:215], v[90:93], v[38:41]
	s_waitcnt lgkmcnt(2)
	v_mfma_f32_16x16x32_bf16 v[42:45], v[216:219], v[90:93], v[42:45]
	v_mfma_f32_16x16x32_bf16 v[46:49], v[146:149], v[208:211], v[46:49]
	v_mfma_f32_16x16x32_bf16 v[26:29], v[194:197], v[208:211], v[26:29]
	v_mfma_f32_16x16x32_bf16 v[14:17], v[212:215], v[208:211], v[14:17]
	v_mfma_f32_16x16x32_bf16 v[10:13], v[216:219], v[208:211], v[10:13]
	s_waitcnt lgkmcnt(0)
	s_barrier
	ds_read_b128 v[220:223], v205 offset:0
	ds_read_b128 v[224:227], v205 offset:2560
	ds_read_b128 v[90:93], v119 offset:0
	ds_read_b128 v[208:211], v119 offset:2560
	v_mfma_f32_16x16x32_bf16 v[34:37], v[146:149], v[138:141], v[34:37]
	v_mfma_f32_16x16x32_bf16 v[22:25], v[194:197], v[138:141], v[22:25]
	v_mfma_f32_16x16x32_bf16 v[18:21], v[212:215], v[138:141], v[18:21]
	v_mfma_f32_16x16x32_bf16 v[62:65], v[216:219], v[138:141], v[62:65]
	ds_read_b128 v[138:141], v205 offset:5120
	v_mfma_f32_16x16x32_bf16 v[50:53], v[212:215], v[142:145], v[50:53]
	ds_read_b128 v[212:215], v119 offset:5120
	v_mfma_f32_16x16x32_bf16 v[2:5], v[216:219], v[142:145], v[2:5]
	ds_read_b128 v[216:219], v119 offset:7680
	v_mfma_f32_16x16x32_bf16 v[58:61], v[146:149], v[142:145], v[58:61]
	v_mfma_f32_16x16x32_bf16 v[54:57], v[194:197], v[142:145], v[54:57]
	ds_read_b128 v[142:145], v205 offset:7680
	ds_read_b128 v[146:149], v119 offset:64
	ds_read_b128 v[194:197], v119 offset:2624
	global_load_dwordx4 v[66:69], v190, s[80:81] offset:768
	global_load_dwordx4 v[70:73], v191, s[80:81] offset:768
	global_load_dwordx4 v[74:77], v190, s[86:87] offset:768
	global_load_dwordx4 v[78:81], v191, s[86:87] offset:768
	global_load_dwordx4 v[82:85], v188, s[96:97] offset:768
	global_load_dwordx4 v[86:89], v188, s[98:99] offset:768
	s_waitcnt lgkmcnt(7)
	v_mfma_f32_16x16x32_bf16 v[6:9], v[90:93], v[220:223], v[6:9]
	s_waitcnt lgkmcnt(6)
	v_mfma_f32_16x16x32_bf16 v[30:33], v[208:211], v[220:223], v[30:33]
	s_waitcnt vmcnt(11)
	ds_write_b128 v207, v[228:231] offset:0
	s_waitcnt lgkmcnt(5)
	v_mfma_f32_16x16x32_bf16 v[38:41], v[212:215], v[220:223], v[38:41]
	s_waitcnt lgkmcnt(4)
	v_mfma_f32_16x16x32_bf16 v[42:45], v[216:219], v[220:223], v[42:45]
	ds_read_b128 v[220:223], v205 offset:64
	v_mfma_f32_16x16x32_bf16 v[46:49], v[90:93], v[224:227], v[46:49]
	s_waitcnt vmcnt(10)
	ds_write_b128 v207, v[232:235] offset:10240
	v_mfma_f32_16x16x32_bf16 v[26:29], v[208:211], v[224:227], v[26:29]
	v_mfma_f32_16x16x32_bf16 v[14:17], v[212:215], v[224:227], v[14:17]
	v_mfma_f32_16x16x32_bf16 v[10:13], v[216:219], v[224:227], v[10:13]
	s_waitcnt vmcnt(9)
	ds_write_b128 v207, v[236:239] offset:20480
	ds_read_b128 v[224:227], v205 offset:2624
	v_mfma_f32_16x16x32_bf16 v[34:37], v[90:93], v[138:141], v[34:37]
	v_mfma_f32_16x16x32_bf16 v[22:25], v[208:211], v[138:141], v[22:25]
	v_mfma_f32_16x16x32_bf16 v[18:21], v[212:215], v[138:141], v[18:21]
	s_waitcnt vmcnt(8)
	ds_write_b128 v207, v[240:243] offset:30720
	v_mfma_f32_16x16x32_bf16 v[62:65], v[216:219], v[138:141], v[62:65]
	ds_read_b128 v[138:141], v205 offset:5184
	s_waitcnt lgkmcnt(9)
	v_mfma_f32_16x16x32_bf16 v[50:53], v[212:215], v[142:145], v[50:53]
	ds_read_b128 v[212:215], v119 offset:5184
	v_mfma_f32_16x16x32_bf16 v[2:5], v[216:219], v[142:145], v[2:5]
	s_waitcnt vmcnt(7)
	ds_write_b128 v0, v[244:247] offset:20480
	ds_read_b128 v[216:219], v119 offset:7744
	v_mfma_f32_16x16x32_bf16 v[58:61], v[90:93], v[142:145], v[58:61]
	v_mfma_f32_16x16x32_bf16 v[54:57], v[208:211], v[142:145], v[54:57]
	ds_read_b128 v[142:145], v205 offset:7744
	s_waitcnt lgkmcnt(9)
	v_mfma_f32_16x16x32_bf16 v[6:9], v[146:149], v[220:223], v[6:9]
	s_waitcnt vmcnt(6)
	ds_write_b128 v0, v[248:251] offset:30720
	v_mfma_f32_16x16x32_bf16 v[30:33], v[194:197], v[220:223], v[30:33]
	s_waitcnt lgkmcnt(4)
	v_mfma_f32_16x16x32_bf16 v[38:41], v[212:215], v[220:223], v[38:41]
	s_waitcnt lgkmcnt(2)
	v_mfma_f32_16x16x32_bf16 v[42:45], v[216:219], v[220:223], v[42:45]
	v_mfma_f32_16x16x32_bf16 v[46:49], v[146:149], v[224:227], v[46:49]
	v_mfma_f32_16x16x32_bf16 v[26:29], v[194:197], v[224:227], v[26:29]
	v_mfma_f32_16x16x32_bf16 v[14:17], v[212:215], v[224:227], v[14:17]
	v_mfma_f32_16x16x32_bf16 v[10:13], v[216:219], v[224:227], v[10:13]
	s_waitcnt lgkmcnt(0)
	s_barrier
	ds_read_b128 v[90:93], v205 offset:40960
	ds_read_b128 v[208:211], v205 offset:43520
	ds_read_b128 v[220:223], v119 offset:20480
	ds_read_b128 v[224:227], v119 offset:23040
	v_mfma_f32_16x16x32_bf16 v[34:37], v[146:149], v[138:141], v[34:37]
	v_mfma_f32_16x16x32_bf16 v[22:25], v[194:197], v[138:141], v[22:25]
	v_mfma_f32_16x16x32_bf16 v[18:21], v[212:215], v[138:141], v[18:21]
	v_mfma_f32_16x16x32_bf16 v[62:65], v[216:219], v[138:141], v[62:65]
	ds_read_b128 v[138:141], v205 offset:46080
	v_mfma_f32_16x16x32_bf16 v[50:53], v[212:215], v[142:145], v[50:53]
	ds_read_b128 v[212:215], v119 offset:25600
	v_mfma_f32_16x16x32_bf16 v[2:5], v[216:219], v[142:145], v[2:5]
	ds_read_b128 v[216:219], v119 offset:28160
	v_mfma_f32_16x16x32_bf16 v[58:61], v[146:149], v[142:145], v[58:61]
	v_mfma_f32_16x16x32_bf16 v[54:57], v[194:197], v[142:145], v[54:57]
	ds_read_b128 v[142:145], v205 offset:48640
	ds_read_b128 v[146:149], v119 offset:20544
	ds_read_b128 v[194:197], v119 offset:23104
	global_load_dwordx4 v[228:231], v190, s[80:81] offset:896
	global_load_dwordx4 v[232:235], v191, s[80:81] offset:896
	global_load_dwordx4 v[236:239], v190, s[86:87] offset:896
	global_load_dwordx4 v[240:243], v191, s[86:87] offset:896
	global_load_dwordx4 v[244:247], v188, s[96:97] offset:896
	global_load_dwordx4 v[248:251], v188, s[98:99] offset:896
	s_waitcnt lgkmcnt(7)
	v_mfma_f32_16x16x32_bf16 v[6:9], v[220:223], v[90:93], v[6:9]
	s_waitcnt lgkmcnt(6)
	v_mfma_f32_16x16x32_bf16 v[30:33], v[224:227], v[90:93], v[30:33]
	s_waitcnt vmcnt(11)
	ds_write_b128 v206, v[66:69] offset:0
	s_waitcnt lgkmcnt(5)
	v_mfma_f32_16x16x32_bf16 v[38:41], v[212:215], v[90:93], v[38:41]
	s_waitcnt lgkmcnt(4)
	v_mfma_f32_16x16x32_bf16 v[42:45], v[216:219], v[90:93], v[42:45]
	ds_read_b128 v[90:93], v205 offset:41024
	v_mfma_f32_16x16x32_bf16 v[46:49], v[220:223], v[208:211], v[46:49]
	s_waitcnt vmcnt(10)
	ds_write_b128 v206, v[70:73] offset:10240
	v_mfma_f32_16x16x32_bf16 v[26:29], v[224:227], v[208:211], v[26:29]
	v_mfma_f32_16x16x32_bf16 v[14:17], v[212:215], v[208:211], v[14:17]
	v_mfma_f32_16x16x32_bf16 v[10:13], v[216:219], v[208:211], v[10:13]
	s_waitcnt vmcnt(9)
	ds_write_b128 v206, v[74:77] offset:20480
	ds_read_b128 v[208:211], v205 offset:43584
	v_mfma_f32_16x16x32_bf16 v[34:37], v[220:223], v[138:141], v[34:37]
	v_mfma_f32_16x16x32_bf16 v[22:25], v[224:227], v[138:141], v[22:25]
	v_mfma_f32_16x16x32_bf16 v[18:21], v[212:215], v[138:141], v[18:21]
	s_waitcnt vmcnt(8)
	ds_write_b128 v206, v[78:81] offset:30720
	v_mfma_f32_16x16x32_bf16 v[62:65], v[216:219], v[138:141], v[62:65]
	ds_read_b128 v[138:141], v205 offset:46144
	s_waitcnt lgkmcnt(9)
	v_mfma_f32_16x16x32_bf16 v[50:53], v[212:215], v[142:145], v[50:53]
	ds_read_b128 v[212:215], v119 offset:25664
	v_mfma_f32_16x16x32_bf16 v[2:5], v[216:219], v[142:145], v[2:5]
	s_waitcnt vmcnt(7)
	ds_write_b128 v0, v[82:85] offset:0
	ds_read_b128 v[216:219], v119 offset:28224
	v_mfma_f32_16x16x32_bf16 v[58:61], v[220:223], v[142:145], v[58:61]
	v_mfma_f32_16x16x32_bf16 v[54:57], v[224:227], v[142:145], v[54:57]
	ds_read_b128 v[142:145], v205 offset:48704
	s_waitcnt lgkmcnt(9)
	v_mfma_f32_16x16x32_bf16 v[6:9], v[146:149], v[90:93], v[6:9]
	s_waitcnt vmcnt(6)
	ds_write_b128 v0, v[86:89] offset:10240
	s_lshl_b32 s10, s66, 10
	s_mov_b32 s11, 0
	v_lshl_add_u64 v[82:83], v[128:129], 0, s[10:11]
	v_lshl_add_u64 v[84:85], v[132:133], 0, s[10:11]
	v_lshl_add_u64 v[86:87], v[152:153], 0, s[10:11]
	v_lshl_add_u64 v[88:89], v[154:155], 0, s[10:11]
	global_load_dwordx2 v[66:67], v[82:83], off
	global_load_dwordx2 v[68:69], v[82:83], off offset:32
	global_load_dwordx2 v[70:71], v[84:85], off
	global_load_dwordx2 v[72:73], v[84:85], off offset:32
	global_load_dwordx2 v[74:75], v[86:87], off
	global_load_dwordx2 v[76:77], v[86:87], off offset:32
	global_load_dwordx2 v[78:79], v[88:89], off
	global_load_dwordx2 v[80:81], v[88:89], off offset:32
	v_mfma_f32_16x16x32_bf16 v[30:33], v[194:197], v[90:93], v[30:33]
	s_waitcnt lgkmcnt(4)
	v_mfma_f32_16x16x32_bf16 v[38:41], v[212:215], v[90:93], v[38:41]
	s_waitcnt lgkmcnt(2)
	v_mfma_f32_16x16x32_bf16 v[42:45], v[216:219], v[90:93], v[42:45]
	v_mfma_f32_16x16x32_bf16 v[46:49], v[146:149], v[208:211], v[46:49]
	v_mfma_f32_16x16x32_bf16 v[26:29], v[194:197], v[208:211], v[26:29]
	v_mfma_f32_16x16x32_bf16 v[14:17], v[212:215], v[208:211], v[14:17]
	v_mfma_f32_16x16x32_bf16 v[10:13], v[216:219], v[208:211], v[10:13]
	s_waitcnt lgkmcnt(0)
	s_barrier
	ds_read_b128 v[220:223], v205 offset:0
	ds_read_b128 v[224:227], v205 offset:2560
	ds_read_b128 v[90:93], v119 offset:0
	ds_read_b128 v[208:211], v119 offset:2560
	v_mfma_f32_16x16x32_bf16 v[34:37], v[146:149], v[138:141], v[34:37]
	v_mfma_f32_16x16x32_bf16 v[22:25], v[194:197], v[138:141], v[22:25]
	v_mfma_f32_16x16x32_bf16 v[18:21], v[212:215], v[138:141], v[18:21]
	v_mfma_f32_16x16x32_bf16 v[62:65], v[216:219], v[138:141], v[62:65]
	ds_read_b128 v[138:141], v205 offset:5120
	v_mfma_f32_16x16x32_bf16 v[50:53], v[212:215], v[142:145], v[50:53]
	ds_read_b128 v[212:215], v119 offset:5120
	v_mfma_f32_16x16x32_bf16 v[2:5], v[216:219], v[142:145], v[2:5]
	ds_read_b128 v[216:219], v119 offset:7680
	v_mfma_f32_16x16x32_bf16 v[58:61], v[146:149], v[142:145], v[58:61]
	v_mfma_f32_16x16x32_bf16 v[54:57], v[194:197], v[142:145], v[54:57]
	ds_read_b128 v[142:145], v205 offset:7680
	ds_read_b128 v[146:149], v119 offset:64
	ds_read_b128 v[194:197], v119 offset:2624
	s_waitcnt lgkmcnt(7)
	v_mfma_f32_16x16x32_bf16 v[6:9], v[90:93], v[220:223], v[6:9]
	s_waitcnt lgkmcnt(6)
	v_mfma_f32_16x16x32_bf16 v[30:33], v[208:211], v[220:223], v[30:33]
	s_waitcnt vmcnt(13)
	ds_write_b128 v207, v[228:231] offset:0
	s_waitcnt lgkmcnt(5)
	v_mfma_f32_16x16x32_bf16 v[38:41], v[212:215], v[220:223], v[38:41]
	s_waitcnt lgkmcnt(4)
	v_mfma_f32_16x16x32_bf16 v[42:45], v[216:219], v[220:223], v[42:45]
	ds_read_b128 v[220:223], v205 offset:64
	v_mfma_f32_16x16x32_bf16 v[46:49], v[90:93], v[224:227], v[46:49]
	s_waitcnt vmcnt(12)
	ds_write_b128 v207, v[232:235] offset:10240
	v_mfma_f32_16x16x32_bf16 v[26:29], v[208:211], v[224:227], v[26:29]
	v_mfma_f32_16x16x32_bf16 v[14:17], v[212:215], v[224:227], v[14:17]
	v_mfma_f32_16x16x32_bf16 v[10:13], v[216:219], v[224:227], v[10:13]
	s_waitcnt vmcnt(11)
	ds_write_b128 v207, v[236:239] offset:20480
	ds_read_b128 v[224:227], v205 offset:2624
	v_mfma_f32_16x16x32_bf16 v[34:37], v[90:93], v[138:141], v[34:37]
	v_mfma_f32_16x16x32_bf16 v[22:25], v[208:211], v[138:141], v[22:25]
	v_mfma_f32_16x16x32_bf16 v[18:21], v[212:215], v[138:141], v[18:21]
	s_waitcnt vmcnt(10)
	ds_write_b128 v207, v[240:243] offset:30720
	v_mfma_f32_16x16x32_bf16 v[62:65], v[216:219], v[138:141], v[62:65]
	ds_read_b128 v[138:141], v205 offset:5184
	s_waitcnt lgkmcnt(9)
	v_mfma_f32_16x16x32_bf16 v[50:53], v[212:215], v[142:145], v[50:53]
	ds_read_b128 v[212:215], v119 offset:5184
	v_mfma_f32_16x16x32_bf16 v[2:5], v[216:219], v[142:145], v[2:5]
	s_waitcnt vmcnt(9)
	ds_write_b128 v0, v[244:247] offset:20480
	ds_read_b128 v[216:219], v119 offset:7744
	v_mfma_f32_16x16x32_bf16 v[58:61], v[90:93], v[142:145], v[58:61]
	v_mfma_f32_16x16x32_bf16 v[54:57], v[208:211], v[142:145], v[54:57]
	ds_read_b128 v[142:145], v205 offset:7744
	s_waitcnt lgkmcnt(9)
	v_mfma_f32_16x16x32_bf16 v[6:9], v[146:149], v[220:223], v[6:9]
	s_waitcnt vmcnt(8)
	ds_write_b128 v0, v[248:251] offset:30720
	v_mfma_f32_16x16x32_bf16 v[30:33], v[194:197], v[220:223], v[30:33]
	s_waitcnt lgkmcnt(4)
	v_mfma_f32_16x16x32_bf16 v[38:41], v[212:215], v[220:223], v[38:41]
	s_waitcnt lgkmcnt(2)
	v_mfma_f32_16x16x32_bf16 v[42:45], v[216:219], v[220:223], v[42:45]
	v_mfma_f32_16x16x32_bf16 v[46:49], v[146:149], v[224:227], v[46:49]
	v_mfma_f32_16x16x32_bf16 v[26:29], v[194:197], v[224:227], v[26:29]
	v_mfma_f32_16x16x32_bf16 v[14:17], v[212:215], v[224:227], v[14:17]
	v_mfma_f32_16x16x32_bf16 v[10:13], v[216:219], v[224:227], v[10:13]
	s_waitcnt lgkmcnt(0)
	s_barrier
	ds_read_b128 v[90:93], v205 offset:40960
	ds_read_b128 v[208:211], v205 offset:43520
	ds_read_b128 v[220:223], v119 offset:20480
	ds_read_b128 v[224:227], v119 offset:23040
	v_mfma_f32_16x16x32_bf16 v[34:37], v[146:149], v[138:141], v[34:37]
	v_mfma_f32_16x16x32_bf16 v[22:25], v[194:197], v[138:141], v[22:25]
	v_mfma_f32_16x16x32_bf16 v[18:21], v[212:215], v[138:141], v[18:21]
	v_mfma_f32_16x16x32_bf16 v[62:65], v[216:219], v[138:141], v[62:65]
	ds_read_b128 v[138:141], v205 offset:46080
	v_mfma_f32_16x16x32_bf16 v[50:53], v[212:215], v[142:145], v[50:53]
	ds_read_b128 v[212:215], v119 offset:25600
	v_mfma_f32_16x16x32_bf16 v[2:5], v[216:219], v[142:145], v[2:5]
	ds_read_b128 v[216:219], v119 offset:28160
	v_mfma_f32_16x16x32_bf16 v[58:61], v[146:149], v[142:145], v[58:61]
	v_mfma_f32_16x16x32_bf16 v[54:57], v[194:197], v[142:145], v[54:57]
	ds_read_b128 v[142:145], v205 offset:48640
	ds_read_b128 v[146:149], v119 offset:20544
	ds_read_b128 v[194:197], v119 offset:23104
	s_waitcnt lgkmcnt(7)
	v_mfma_f32_16x16x32_bf16 v[6:9], v[220:223], v[90:93], v[6:9]
	s_waitcnt lgkmcnt(6)
	v_mfma_f32_16x16x32_bf16 v[30:33], v[224:227], v[90:93], v[30:33]
	s_waitcnt lgkmcnt(4)
	v_mfma_f32_16x16x32_bf16 v[38:41], v[212:215], v[90:93], v[38:41]
	s_waitcnt lgkmcnt(3)
	v_mfma_f32_16x16x32_bf16 v[42:45], v[216:219], v[90:93], v[42:45]
	ds_read_b128 v[90:93], v205 offset:41024
	v_mfma_f32_16x16x32_bf16 v[46:49], v[220:223], v[208:211], v[46:49]
	v_mfma_f32_16x16x32_bf16 v[26:29], v[224:227], v[208:211], v[26:29]
	v_mfma_f32_16x16x32_bf16 v[14:17], v[212:215], v[208:211], v[14:17]
	v_mfma_f32_16x16x32_bf16 v[10:13], v[216:219], v[208:211], v[10:13]
	ds_read_b128 v[208:211], v205 offset:43584
	v_mfma_f32_16x16x32_bf16 v[34:37], v[220:223], v[138:141], v[34:37]
	v_mfma_f32_16x16x32_bf16 v[22:25], v[224:227], v[138:141], v[22:25]
	v_mfma_f32_16x16x32_bf16 v[18:21], v[212:215], v[138:141], v[18:21]
	v_mfma_f32_16x16x32_bf16 v[62:65], v[216:219], v[138:141], v[62:65]
	ds_read_b128 v[138:141], v205 offset:46144
	s_waitcnt lgkmcnt(5)
	v_mfma_f32_16x16x32_bf16 v[50:53], v[212:215], v[142:145], v[50:53]
	ds_read_b128 v[212:215], v119 offset:25664
	v_mfma_f32_16x16x32_bf16 v[2:5], v[216:219], v[142:145], v[2:5]
	ds_read_b128 v[216:219], v119 offset:28224
	v_mfma_f32_16x16x32_bf16 v[58:61], v[220:223], v[142:145], v[58:61]
	v_mfma_f32_16x16x32_bf16 v[54:57], v[224:227], v[142:145], v[54:57]
	ds_read_b128 v[142:145], v205 offset:48704
	s_waitcnt lgkmcnt(5)
	v_mfma_f32_16x16x32_bf16 v[6:9], v[146:149], v[90:93], v[6:9]
	s_waitcnt vmcnt(0)
	v_mfma_f32_16x16x32_bf16 v[30:33], v[194:197], v[90:93], v[30:33]
	s_waitcnt lgkmcnt(2)
	v_mfma_f32_16x16x32_bf16 v[38:41], v[212:215], v[90:93], v[38:41]
	s_waitcnt lgkmcnt(1)
	v_mfma_f32_16x16x32_bf16 v[42:45], v[216:219], v[90:93], v[42:45]
	v_cvt_f32_ubyte0_e32 v86, v66
	v_cvt_f32_ubyte1_e32 v87, v66
	v_cvt_f32_ubyte2_e32 v88, v66
	v_cvt_f32_ubyte3_e32 v89, v66
	v_mul_f32_e32 v86, s34, v86
	v_mul_f32_e32 v87, s34, v87
	v_mul_f32_e32 v88, s34, v88
	v_mul_f32_e32 v89, s34, v89
	v_fma_f32 v184, v6, v86, v184
	v_fma_f32 v185, v7, v87, v185
	v_fma_f32 v186, v8, v88, v186
	v_fma_f32 v187, v9, v89, v187
	v_mfma_f32_16x16x32_bf16 v[46:49], v[146:149], v[208:211], v[46:49]
	v_cvt_f32_ubyte0_e32 v82, v67
	v_cvt_f32_ubyte1_e32 v83, v67
	v_cvt_f32_ubyte2_e32 v84, v67
	v_cvt_f32_ubyte3_e32 v85, v67
	v_mul_f32_e32 v82, s34, v82
	v_mul_f32_e32 v83, s34, v83
	v_mul_f32_e32 v84, s34, v84
	v_mul_f32_e32 v85, s34, v85
	v_fma_f32 v180, v30, v82, v180
	v_fma_f32 v181, v31, v83, v181
	v_fma_f32 v182, v32, v84, v182
	v_fma_f32 v183, v33, v85, v183
	v_mfma_f32_16x16x32_bf16 v[26:29], v[194:197], v[208:211], v[26:29]
	v_cvt_f32_ubyte0_e32 v86, v68
	v_cvt_f32_ubyte1_e32 v87, v68
	v_cvt_f32_ubyte2_e32 v88, v68
	v_cvt_f32_ubyte3_e32 v89, v68
	v_mul_f32_e32 v86, s34, v86
	v_mul_f32_e32 v87, s34, v87
	v_mul_f32_e32 v88, s34, v88
	v_mul_f32_e32 v89, s34, v89
	v_fma_f32 v176, v38, v86, v176
	v_fma_f32 v177, v39, v87, v177
	v_fma_f32 v178, v40, v88, v178
	v_fma_f32 v179, v41, v89, v179
	v_mfma_f32_16x16x32_bf16 v[14:17], v[212:215], v[208:211], v[14:17]
	v_cvt_f32_ubyte0_e32 v82, v69
	v_cvt_f32_ubyte1_e32 v83, v69
	v_cvt_f32_ubyte2_e32 v84, v69
	v_cvt_f32_ubyte3_e32 v85, v69
	v_mul_f32_e32 v82, s34, v82
	v_mul_f32_e32 v83, s34, v83
	v_mul_f32_e32 v84, s34, v84
	v_mul_f32_e32 v85, s34, v85
	v_fma_f32 v172, v42, v82, v172
	v_fma_f32 v173, v43, v83, v173
	v_fma_f32 v174, v44, v84, v174
	v_fma_f32 v175, v45, v85, v175
	v_mfma_f32_16x16x32_bf16 v[10:13], v[216:219], v[208:211], v[10:13]
	v_cvt_f32_ubyte0_e32 v86, v70
	v_cvt_f32_ubyte1_e32 v87, v70
	v_cvt_f32_ubyte2_e32 v88, v70
	v_cvt_f32_ubyte3_e32 v89, v70
	v_mul_f32_e32 v86, s34, v86
	v_mul_f32_e32 v87, s34, v87
	v_mul_f32_e32 v88, s34, v88
	v_mul_f32_e32 v89, s34, v89
	v_fma_f32 v168, v46, v86, v168
	v_fma_f32 v169, v47, v87, v169
	v_fma_f32 v170, v48, v88, v170
	v_fma_f32 v171, v49, v89, v171
	v_mfma_f32_16x16x32_bf16 v[34:37], v[146:149], v[138:141], v[34:37]
	v_cvt_f32_ubyte0_e32 v82, v71
	v_cvt_f32_ubyte1_e32 v83, v71
	v_cvt_f32_ubyte2_e32 v84, v71
	v_cvt_f32_ubyte3_e32 v85, v71
	v_mul_f32_e32 v82, s34, v82
	v_mul_f32_e32 v83, s34, v83
	v_mul_f32_e32 v84, s34, v84
	v_mul_f32_e32 v85, s34, v85
	v_fma_f32 v164, v26, v82, v164
	v_fma_f32 v165, v27, v83, v165
	v_fma_f32 v166, v28, v84, v166
	v_fma_f32 v167, v29, v85, v167
	v_mfma_f32_16x16x32_bf16 v[22:25], v[194:197], v[138:141], v[22:25]
	v_cvt_f32_ubyte0_e32 v86, v72
	v_cvt_f32_ubyte1_e32 v87, v72
	v_cvt_f32_ubyte2_e32 v88, v72
	v_cvt_f32_ubyte3_e32 v89, v72
	v_mul_f32_e32 v86, s34, v86
	v_mul_f32_e32 v87, s34, v87
	v_mul_f32_e32 v88, s34, v88
	v_mul_f32_e32 v89, s34, v89
	v_fma_f32 v160, v14, v86, v160
	v_fma_f32 v161, v15, v87, v161
	v_fma_f32 v162, v16, v88, v162
	v_fma_f32 v163, v17, v89, v163
	v_mfma_f32_16x16x32_bf16 v[18:21], v[212:215], v[138:141], v[18:21]
	v_cvt_f32_ubyte0_e32 v82, v73
	v_cvt_f32_ubyte1_e32 v83, v73
	v_cvt_f32_ubyte2_e32 v84, v73
	v_cvt_f32_ubyte3_e32 v85, v73
	v_mul_f32_e32 v82, s34, v82
	v_mul_f32_e32 v83, s34, v83
	v_mul_f32_e32 v84, s34, v84
	v_mul_f32_e32 v85, s34, v85
	v_fma_f32 v156, v10, v82, v156
	v_fma_f32 v157, v11, v83, v157
	v_fma_f32 v158, v12, v84, v158
	v_fma_f32 v159, v13, v85, v159
	v_mfma_f32_16x16x32_bf16 v[62:65], v[216:219], v[138:141], v[62:65]
	v_cvt_f32_ubyte0_e32 v86, v74
	v_cvt_f32_ubyte1_e32 v87, v74
	v_cvt_f32_ubyte2_e32 v88, v74
	v_cvt_f32_ubyte3_e32 v89, v74
	v_mul_f32_e32 v86, s34, v86
	v_mul_f32_e32 v87, s34, v87
	v_mul_f32_e32 v88, s34, v88
	v_mul_f32_e32 v89, s34, v89
	v_fma_f32 v136, v34, v86, v136
	v_fma_f32 v137, v35, v87, v137
	v_fma_f32 v150, v36, v88, v150
	v_fma_f32 v151, v37, v89, v151
	s_waitcnt lgkmcnt(0)
	v_mfma_f32_16x16x32_bf16 v[50:53], v[212:215], v[142:145], v[50:53]
	v_cvt_f32_ubyte0_e32 v82, v75
	v_cvt_f32_ubyte1_e32 v83, v75
	v_cvt_f32_ubyte2_e32 v84, v75
	v_cvt_f32_ubyte3_e32 v85, v75
	v_mul_f32_e32 v82, s34, v82
	v_mul_f32_e32 v83, s34, v83
	v_mul_f32_e32 v84, s34, v84
	v_mul_f32_e32 v85, s34, v85
	v_fma_f32 v130, v22, v82, v130
	v_fma_f32 v131, v23, v83, v131
	v_fma_f32 v134, v24, v84, v134
	v_fma_f32 v135, v25, v85, v135
	v_mfma_f32_16x16x32_bf16 v[2:5], v[216:219], v[142:145], v[2:5]
	v_cvt_f32_ubyte0_e32 v86, v76
	v_cvt_f32_ubyte1_e32 v87, v76
	v_cvt_f32_ubyte2_e32 v88, v76
	v_cvt_f32_ubyte3_e32 v89, v76
	v_mul_f32_e32 v86, s34, v86
	v_mul_f32_e32 v87, s34, v87
	v_mul_f32_e32 v88, s34, v88
	v_mul_f32_e32 v89, s34, v89
	v_fma_f32 v124, v18, v86, v124
	v_fma_f32 v125, v19, v87, v125
	v_fma_f32 v126, v20, v88, v126
	v_fma_f32 v127, v21, v89, v127
	v_mfma_f32_16x16x32_bf16 v[58:61], v[146:149], v[142:145], v[58:61]
	v_cvt_f32_ubyte0_e32 v82, v77
	v_cvt_f32_ubyte1_e32 v83, v77
	v_cvt_f32_ubyte2_e32 v84, v77
	v_cvt_f32_ubyte3_e32 v85, v77
	v_mul_f32_e32 v82, s34, v82
	v_mul_f32_e32 v83, s34, v83
	v_mul_f32_e32 v84, s34, v84
	v_mul_f32_e32 v85, s34, v85
	v_fma_f32 v120, v62, v82, v120
	v_fma_f32 v121, v63, v83, v121
	v_fma_f32 v122, v64, v84, v122
	v_fma_f32 v123, v65, v85, v123
	v_mfma_f32_16x16x32_bf16 v[54:57], v[194:197], v[142:145], v[54:57]
	v_cvt_f32_ubyte0_e32 v86, v80
	v_cvt_f32_ubyte1_e32 v87, v80
	v_cvt_f32_ubyte2_e32 v88, v80
	v_cvt_f32_ubyte3_e32 v89, v80
	v_mul_f32_e32 v86, s34, v86
	v_mul_f32_e32 v87, s34, v87
	v_mul_f32_e32 v88, s34, v88
	v_mul_f32_e32 v89, s34, v89
	v_fma_f32 v100, v50, v86, v100
	v_fma_f32 v101, v51, v87, v101
	v_fma_f32 v102, v52, v88, v102
	v_fma_f32 v103, v53, v89, v103
	s_nop 7
	s_nop 3
	v_cvt_f32_ubyte0_e32 v86, v81
	v_cvt_f32_ubyte1_e32 v87, v81
	v_cvt_f32_ubyte2_e32 v88, v81
	v_cvt_f32_ubyte3_e32 v89, v81
	v_mul_f32_e32 v86, s34, v86
	v_mul_f32_e32 v87, s34, v87
	v_mul_f32_e32 v88, s34, v88
	v_mul_f32_e32 v89, s34, v89
	v_fma_f32 v96, v2, v86, v96
	v_fma_f32 v97, v3, v87, v97
	v_fma_f32 v98, v4, v88, v98
	v_fma_f32 v99, v5, v89, v99
	v_cvt_f32_ubyte0_e32 v82, v78
	v_cvt_f32_ubyte1_e32 v83, v78
	v_cvt_f32_ubyte2_e32 v84, v78
	v_cvt_f32_ubyte3_e32 v85, v78
	v_mul_f32_e32 v82, s34, v82
	v_mul_f32_e32 v83, s34, v83
	v_mul_f32_e32 v84, s34, v84
	v_mul_f32_e32 v85, s34, v85
	v_fma_f32 v114, v58, v82, v114
	v_fma_f32 v115, v59, v83, v115
	v_fma_f32 v116, v60, v84, v116
	v_fma_f32 v117, v61, v85, v117
	v_cvt_f32_ubyte0_e32 v86, v79
	v_cvt_f32_ubyte1_e32 v87, v79
	v_cvt_f32_ubyte2_e32 v88, v79
	v_cvt_f32_ubyte3_e32 v89, v79
	v_mul_f32_e32 v86, s34, v86
	v_mul_f32_e32 v87, s34, v87
	v_mul_f32_e32 v88, s34, v88
	v_mul_f32_e32 v89, s34, v89
	v_fma_f32 v106, v54, v86, v106
	v_fma_f32 v107, v55, v87, v107
	v_fma_f32 v108, v56, v88, v108
	v_fma_f32 v109, v57, v89, v109
	s_add_i32 s66, s66, 1
	s_add_u32 s6, s6, 0x100000
	s_addc_u32 s7, s7, 0
	s_cmp_eq_u32 s66, 4
	s_cbranch_scc0 .LBB0_1004
	v_mov_b32_e32 v138, 0xa00
	v_mov_b32_e32 v139, 0x0
	v_mov_b32_e32 v140, 0x9ff
	v_mov_b32_e32 v141, 0x0
	v_mov_b32_e32 v142, 0x200
	v_mov_b32_e32 v143, 0x0
	v_mov_b32_e32 v144, 0x1ff
	v_mov_b32_e32 v145, 0x0
	v_mov_b32_e32 v146, 0xb00
	v_mov_b32_e32 v147, 0x0
	v_mov_b32_e32 v148, 0xaff
	v_mov_b32_e32 v149, 0x0
	v_mov_b32_e32 v194, 0x358637bd
	v_mov_b32_e32 v195, 0x2000
	v_mov_b32_e32 v196, 0x3e38aa3b
	v_mov_b32_e32 v197, 0x41b17218
	v_lshlrev_b32_e32 v0, 1, v118
	v_lshl_add_u64 v[6:7], s[4:5], 0, v[0:1]
	v_lshlrev_b64 v[2:3], 11, v[112:113]
	v_lshl_add_u64 v[8:9], v[6:7], 0, v[2:3]
	v_cvt_pk_bf16_f32 v2, v184, v185
	v_cvt_pk_bf16_f32 v3, v186, v187
	v_cvt_pk_bf16_f32 v4, v180, v181
	v_cvt_pk_bf16_f32 v5, v182, v183
	global_store_dwordx4 v[8:9], v[2:5], off
	v_readlane_b32 s46, v254, 29
	s_mov_b32 s38, 0
	v_cvt_pk_bf16_f32 v2, v176, v177
	v_cvt_pk_bf16_f32 v3, v178, v179
	v_cvt_pk_bf16_f32 v4, v172, v173
	v_cvt_pk_bf16_f32 v5, v174, v175
	global_store_dwordx4 v[8:9], v[2:5], off offset:64
	v_readlane_b32 s47, v254, 30
	s_nop 0
	v_lshlrev_b64 v[2:3], 11, v[110:111]
	v_lshl_add_u64 v[8:9], v[6:7], 0, v[2:3]
	v_cvt_pk_bf16_f32 v2, v168, v169
	v_cvt_pk_bf16_f32 v3, v170, v171
	v_cvt_pk_bf16_f32 v4, v164, v165
	v_cvt_pk_bf16_f32 v5, v166, v167
	global_store_dwordx4 v[8:9], v[2:5], off
	s_nop 1
	v_cvt_pk_bf16_f32 v2, v160, v161
	v_cvt_pk_bf16_f32 v3, v162, v163
	v_cvt_pk_bf16_f32 v4, v156, v157
	v_cvt_pk_bf16_f32 v5, v158, v159
	global_store_dwordx4 v[8:9], v[2:5], off offset:64
	s_nop 1
	v_lshlrev_b64 v[2:3], 11, v[104:105]
	v_lshl_add_u64 v[8:9], v[6:7], 0, v[2:3]
	v_cvt_pk_bf16_f32 v2, v136, v137
	v_cvt_pk_bf16_f32 v3, v150, v151
	v_cvt_pk_bf16_f32 v4, v130, v131
	v_cvt_pk_bf16_f32 v5, v134, v135
	global_store_dwordx4 v[8:9], v[2:5], off
	s_nop 1
	v_cvt_pk_bf16_f32 v2, v124, v125
	v_cvt_pk_bf16_f32 v3, v126, v127
	v_cvt_pk_bf16_f32 v4, v120, v121
	v_cvt_pk_bf16_f32 v5, v122, v123
	global_store_dwordx4 v[8:9], v[2:5], off offset:64
	s_nop 1
	v_lshlrev_b64 v[2:3], 11, v[94:95]
	v_lshl_add_u64 v[6:7], v[6:7], 0, v[2:3]
	v_cvt_pk_bf16_f32 v2, v114, v115
	v_cvt_pk_bf16_f32 v3, v116, v117
	v_cvt_pk_bf16_f32 v4, v106, v107
	v_cvt_pk_bf16_f32 v5, v108, v109
	global_store_dwordx4 v[6:7], v[2:5], off
	s_nop 1
	v_cvt_pk_bf16_f32 v2, v100, v101
	v_cvt_pk_bf16_f32 v3, v102, v103
	v_cvt_pk_bf16_f32 v4, v96, v97
	v_cvt_pk_bf16_f32 v5, v98, v99
	global_store_dwordx4 v[6:7], v[2:5], off offset:64
